# attention unit: static s_setprio 1 for waves 4-7 during the unit, reset to 0 at unit epilogue
# speedup vs baseline: 1.0026x; 1.0026x over previous
.LBB0_1975:
	s_or_b64 exec, exec, s[2:3]
	s_setprio 0
	s_waitcnt lgkmcnt(0)
	s_mul_i32 s45, s45, 0x4100000
	ds_read_b128 v[4:7], v2 offset:128
	ds_read_b128 v[8:11], v2 offset:160
	s_add_u32 s2, s41, s45
	s_addc_u32 s3, s42, 0
	s_lshl_b64 s[0:1], s[0:1], 1
	s_add_u32 s0, s2, s0
	s_addc_u32 s1, s3, s1
	s_lshl_b32 s2, s53, 1
	s_add_u32 s0, s0, s2
	s_waitcnt lgkmcnt(1)
	v_rcp_f32_e32 v12, v4
	v_rcp_f32_e32 v13, v5
	v_rcp_f32_e32 v14, v6
	v_rcp_f32_e32 v15, v7
	s_waitcnt lgkmcnt(0)
	v_rcp_f32_e32 v80, v8
	ds_read_b128 v[4:7], v2 offset:192
	v_rcp_f32_e32 v81, v9
	v_rcp_f32_e32 v82, v10
	v_rcp_f32_e32 v83, v11
	ds_read_b128 v[8:11], v2 offset:224
	s_addc_u32 s1, s1, 0
	s_lshl_b32 s2, s44, 12
	s_add_i32 s2, s2, 0
	s_add_i32 s2, s2, 0x12800
	v_lshlrev_b32_e32 v0, 9, v243
	v_lshlrev_b32_e32 v2, 1, v242
	v_add3_u32 v92, s2, v0, v2
	v_lshlrev_b32_e32 v0, 1, v244
	v_and_b32_e32 v0, 0x70, v0
	s_waitcnt lgkmcnt(0)
	v_rcp_f32_e32 v90, v10
	v_rcp_f32_e32 v91, v11
	v_add_u32_e32 v94, s2, v0
	v_lshl_add_u64 v[10:11], s[0:1], 0, v[0:1]
	v_mul_f32_e32 v0, v64, v12
	v_cvt_pk_bf16_f32 v0, v0, s0
	ds_write_b16 v92, v0
	v_mul_f32_e32 v0, v48, v12
	v_cvt_pk_bf16_f32 v0, v0, s0
	ds_write_b16 v92, v0 offset:64
	v_mul_f32_e32 v0, v65, v13
	v_cvt_pk_bf16_f32 v0, v0, s0
	ds_write_b16 v92, v0 offset:128
	v_mul_f32_e32 v0, v49, v13
	v_cvt_pk_bf16_f32 v0, v0, s0
	ds_write_b16 v92, v0 offset:192
	v_mul_f32_e32 v0, v66, v14
	v_cvt_pk_bf16_f32 v0, v0, s0
	ds_write_b16 v92, v0 offset:256
	v_mul_f32_e32 v0, v50, v14
	v_cvt_pk_bf16_f32 v0, v0, s0
	ds_write_b16 v92, v0 offset:320
	v_mul_f32_e32 v0, v67, v15
	v_cvt_pk_bf16_f32 v0, v0, s0
	ds_write_b16 v92, v0 offset:384
	v_mul_f32_e32 v0, v51, v15
	v_cvt_pk_bf16_f32 v0, v0, s0
	ds_write_b16 v92, v0 offset:448
	v_mul_f32_e32 v0, v68, v80
	v_cvt_pk_bf16_f32 v0, v0, s0
	ds_write_b16 v92, v0 offset:1024
	v_mul_f32_e32 v0, v52, v80
	v_cvt_pk_bf16_f32 v0, v0, s0
	ds_write_b16 v92, v0 offset:1088
	v_mul_f32_e32 v0, v69, v81
	v_cvt_pk_bf16_f32 v0, v0, s0
	ds_write_b16 v92, v0 offset:1152
	v_mul_f32_e32 v0, v53, v81
	v_cvt_pk_bf16_f32 v0, v0, s0
	ds_write_b16 v92, v0 offset:1216
	v_mul_f32_e32 v0, v70, v82
	v_cvt_pk_bf16_f32 v0, v0, s0
	ds_write_b16 v92, v0 offset:1280
	v_mul_f32_e32 v0, v54, v82
	v_cvt_pk_bf16_f32 v0, v0, s0
	v_rcp_f32_e32 v84, v4
	ds_write_b16 v92, v0 offset:1344
	v_mul_f32_e32 v0, v71, v83
	v_cvt_pk_bf16_f32 v0, v0, s0
	ds_write_b16 v92, v0 offset:1408
	v_mul_f32_e32 v0, v55, v83
	v_cvt_pk_bf16_f32 v0, v0, s0
	v_rcp_f32_e32 v85, v5
	ds_write_b16 v92, v0 offset:1472
	v_mul_f32_e32 v0, v72, v84
	v_cvt_pk_bf16_f32 v0, v0, s0
	ds_write_b16 v92, v0 offset:2048
	v_mul_f32_e32 v0, v56, v84
	v_cvt_pk_bf16_f32 v0, v0, s0
	v_rcp_f32_e32 v86, v6
	ds_write_b16 v92, v0 offset:2112
	v_mul_f32_e32 v0, v73, v85
	v_cvt_pk_bf16_f32 v0, v0, s0
	ds_write_b16 v92, v0 offset:2176
	v_mul_f32_e32 v0, v57, v85
	v_cvt_pk_bf16_f32 v0, v0, s0
	v_rcp_f32_e32 v87, v7
	ds_write_b16 v92, v0 offset:2240
	v_mul_f32_e32 v0, v74, v86
	v_cvt_pk_bf16_f32 v0, v0, s0
	ds_write_b16 v92, v0 offset:2304
	v_mul_f32_e32 v0, v58, v86
	v_cvt_pk_bf16_f32 v0, v0, s0
	v_rcp_f32_e32 v88, v8
	ds_write_b16 v92, v0 offset:2368
	v_mul_f32_e32 v0, v75, v87
	v_cvt_pk_bf16_f32 v0, v0, s0
	ds_write_b16 v92, v0 offset:2432
	v_mul_f32_e32 v0, v59, v87
	v_cvt_pk_bf16_f32 v0, v0, s0
	v_rcp_f32_e32 v89, v9
	ds_write_b16 v92, v0 offset:2496
	v_mul_f32_e32 v0, v76, v88
	v_cvt_pk_bf16_f32 v0, v0, s0
	ds_write_b16 v92, v0 offset:3072
	v_mul_f32_e32 v0, v60, v88
	v_cvt_pk_bf16_f32 v0, v0, s0
	ds_write_b16 v92, v0 offset:3136
	v_mul_f32_e32 v0, v77, v89
	v_cvt_pk_bf16_f32 v0, v0, s0
	ds_write_b16 v92, v0 offset:3200
	v_mul_f32_e32 v0, v61, v89
	v_cvt_pk_bf16_f32 v0, v0, s0
	ds_write_b16 v92, v0 offset:3264
	v_mul_f32_e32 v0, v78, v90
	v_cvt_pk_bf16_f32 v0, v0, s0
	ds_write_b16 v92, v0 offset:3328
	v_mul_f32_e32 v0, v62, v90
	v_cvt_pk_bf16_f32 v0, v0, s0
	ds_write_b16 v92, v0 offset:3392
	v_mul_f32_e32 v0, v79, v91
	v_cvt_pk_bf16_f32 v0, v0, s0
	ds_write_b16 v92, v0 offset:3456
	v_mul_f32_e32 v0, v63, v91
	v_lshrrev_b32_e32 v93, 3, v241
	v_cvt_pk_bf16_f32 v0, v0, s0
	ds_write_b16 v92, v0 offset:3520
	v_or_b32_e32 v50, 8, v93
	v_lshl_add_u32 v95, v93, 7, v94
	s_waitcnt lgkmcnt(0)
	v_lshl_add_u32 v56, v50, 7, v94
	ds_read_b128 v[2:5], v95
	ds_read_b128 v[6:9], v56
	v_lshlrev_b32_e32 v0, 11, v93
	v_lshl_add_u64 v[48:49], v[10:11], 0, v[0:1]
	v_lshlrev_b32_e32 v0, 11, v50
	v_lshl_add_u64 v[50:51], v[10:11], 0, v[0:1]
	v_or_b32_e32 v0, 16, v93
	v_or_b32_e32 v54, 24, v93
	v_lshl_add_u32 v57, v0, 7, v94
	v_lshl_add_u32 v58, v54, 7, v94
	s_waitcnt lgkmcnt(1)
	global_store_dwordx4 v[48:49], v[2:5], off
	ds_read_b128 v[2:5], v57
	s_waitcnt lgkmcnt(1)
	global_store_dwordx4 v[50:51], v[6:9], off
	ds_read_b128 v[6:9], v58
	v_lshlrev_b32_e32 v0, 11, v0
	v_lshl_add_u64 v[52:53], v[10:11], 0, v[0:1]
	v_lshlrev_b32_e32 v0, 11, v54
	v_lshl_add_u64 v[54:55], v[10:11], 0, v[0:1]
	v_mul_f32_e32 v0, v32, v12
	s_waitcnt lgkmcnt(1)
	global_store_dwordx4 v[52:53], v[2:5], off
	s_waitcnt lgkmcnt(0)
	global_store_dwordx4 v[54:55], v[6:9], off
	v_cvt_pk_bf16_f32 v0, v0, s0
	s_waitcnt lgkmcnt(0)
	ds_write_b16 v92, v0
	v_mul_f32_e32 v0, v16, v12
	v_cvt_pk_bf16_f32 v0, v0, s0
	ds_write_b16 v92, v0 offset:64
	v_mul_f32_e32 v0, v33, v13
	v_cvt_pk_bf16_f32 v0, v0, s0
	ds_write_b16 v92, v0 offset:128
	v_mul_f32_e32 v0, v17, v13
	v_cvt_pk_bf16_f32 v0, v0, s0
	ds_write_b16 v92, v0 offset:192
	v_mul_f32_e32 v0, v34, v14
	v_cvt_pk_bf16_f32 v0, v0, s0
	ds_write_b16 v92, v0 offset:256
	v_mul_f32_e32 v0, v18, v14
	v_cvt_pk_bf16_f32 v0, v0, s0
	ds_write_b16 v92, v0 offset:320
	v_mul_f32_e32 v0, v35, v15
	v_cvt_pk_bf16_f32 v0, v0, s0
	ds_write_b16 v92, v0 offset:384
	v_mul_f32_e32 v0, v19, v15
	v_cvt_pk_bf16_f32 v0, v0, s0
	ds_write_b16 v92, v0 offset:448
	v_mul_f32_e32 v0, v36, v80
	v_cvt_pk_bf16_f32 v0, v0, s0
	ds_write_b16 v92, v0 offset:1024
	v_mul_f32_e32 v0, v20, v80
	v_cvt_pk_bf16_f32 v0, v0, s0
	ds_write_b16 v92, v0 offset:1088
	v_mul_f32_e32 v0, v37, v81
	v_cvt_pk_bf16_f32 v0, v0, s0
	ds_write_b16 v92, v0 offset:1152
	v_mul_f32_e32 v0, v21, v81
	v_cvt_pk_bf16_f32 v0, v0, s0
	ds_write_b16 v92, v0 offset:1216
	v_mul_f32_e32 v0, v38, v82
	v_cvt_pk_bf16_f32 v0, v0, s0
	ds_write_b16 v92, v0 offset:1280
	v_mul_f32_e32 v0, v22, v82
	v_cvt_pk_bf16_f32 v0, v0, s0
	ds_write_b16 v92, v0 offset:1344
	v_mul_f32_e32 v0, v39, v83
	v_cvt_pk_bf16_f32 v0, v0, s0
	ds_write_b16 v92, v0 offset:1408
	v_mul_f32_e32 v0, v23, v83
	v_cvt_pk_bf16_f32 v0, v0, s0
	ds_write_b16 v92, v0 offset:1472
	v_mul_f32_e32 v0, v40, v84
	v_cvt_pk_bf16_f32 v0, v0, s0
	ds_write_b16 v92, v0 offset:2048
	v_mul_f32_e32 v0, v24, v84
	v_cvt_pk_bf16_f32 v0, v0, s0
	ds_write_b16 v92, v0 offset:2112
	v_mul_f32_e32 v0, v41, v85
	v_cvt_pk_bf16_f32 v0, v0, s0
	ds_write_b16 v92, v0 offset:2176
	v_mul_f32_e32 v0, v25, v85
	v_cvt_pk_bf16_f32 v0, v0, s0
	ds_write_b16 v92, v0 offset:2240
	v_mul_f32_e32 v0, v42, v86
	v_cvt_pk_bf16_f32 v0, v0, s0
	ds_write_b16 v92, v0 offset:2304
	v_mul_f32_e32 v0, v26, v86
	v_cvt_pk_bf16_f32 v0, v0, s0
	ds_write_b16 v92, v0 offset:2368
	v_mul_f32_e32 v0, v43, v87
	v_cvt_pk_bf16_f32 v0, v0, s0
	ds_write_b16 v92, v0 offset:2432
	v_mul_f32_e32 v0, v27, v87
	v_cvt_pk_bf16_f32 v0, v0, s0
	ds_write_b16 v92, v0 offset:2496
	v_mul_f32_e32 v0, v44, v88
	v_cvt_pk_bf16_f32 v0, v0, s0
	ds_write_b16 v92, v0 offset:3072
	v_mul_f32_e32 v0, v28, v88
	v_cvt_pk_bf16_f32 v0, v0, s0
	ds_write_b16 v92, v0 offset:3136
	v_mul_f32_e32 v0, v45, v89
	v_cvt_pk_bf16_f32 v0, v0, s0
	ds_write_b16 v92, v0 offset:3200
	v_mul_f32_e32 v0, v29, v89
	v_cvt_pk_bf16_f32 v0, v0, s0
	ds_write_b16 v92, v0 offset:3264
	v_mul_f32_e32 v0, v46, v90
	v_cvt_pk_bf16_f32 v0, v0, s0
	ds_write_b16 v92, v0 offset:3328
	v_mul_f32_e32 v0, v30, v90
	v_cvt_pk_bf16_f32 v0, v0, s0
	ds_write_b16 v92, v0 offset:3392
	v_mul_f32_e32 v0, v47, v91
	v_cvt_pk_bf16_f32 v0, v0, s0
	ds_write_b16 v92, v0 offset:3456
	v_mul_f32_e32 v0, v31, v91
	v_cvt_pk_bf16_f32 v0, v0, s0
	ds_write_b16 v92, v0 offset:3520
	s_waitcnt lgkmcnt(0)
	ds_read_b128 v[2:5], v95
	ds_read_b128 v[6:9], v56
	ds_read_b128 v[10:13], v57
	ds_read_b128 v[14:17], v58
	s_waitcnt lgkmcnt(3)
	global_store_dwordx4 v[48:49], v[2:5], off offset:128
	s_waitcnt lgkmcnt(2)
	global_store_dwordx4 v[50:51], v[6:9], off offset:128
	s_waitcnt lgkmcnt(1)
	global_store_dwordx4 v[52:53], v[10:13], off offset:128
	s_waitcnt lgkmcnt(0)
	global_store_dwordx4 v[54:55], v[14:17], off offset:128
	s_waitcnt lgkmcnt(0)
	s_waitcnt lgkmcnt(0)
	s_barrier

.LBB0_1984:
	s_or_b64 exec, exec, s[0:1]
	v_readlane_b32 s0, v253, 25
	s_waitcnt vmcnt(0) lgkmcnt(0)
	s_barrier
	v_mov_b32_e32 v0, s0
	ds_read_b32 v0, v0
	s_waitcnt lgkmcnt(0)
	s_barrier
	v_readfirstlane_b32 s0, v0
	s_cmp_lt_i32 s0, 0
	s_cbranch_scc1 .LBB0_2003
	s_getreg_b32 s1, hwreg(HW_REG_HW_ID, 0, 7)
	s_and_b32 s1, s1, 63
	s_lshl_b32 s1, s1, 2
	s_add_i32 s1, s1, 0x22240
	v_mov_b32_e32 v0, s1
	ds_read_b32 v0, v0
	v_mbcnt_lo_u32_b32 v34, -1, 0
	v_mbcnt_hi_u32_b32 v34, -1, v34
	s_bfe_u32 s27, s0, 0x50001
	s_and_b32 s45, s0, 1
	s_lshr_b32 s1, s0, 15
	s_waitcnt lgkmcnt(0)
	v_lshl_or_b32 v4, v0, 6, v34
	s_lshl_b32 s0, s0, 7
	v_readfirstlane_b32 s47, v4
	s_ashr_i32 s44, s47, 6
	s_cmp_ge_u32 s44, 4
	s_cbranch_scc0 .Lprio_skip
	s_setprio 1
.Lprio_skip:
	s_and_b32 s20, s0, 0x7fe000
	s_lshl_b32 s0, s27, 8
	s_and_b32 s26, s1, 0xfffe
	s_xor_b32 s19, s0, 0x1f00
	s_lshl_b32 s1, s44, 5
	s_or_b32 s18, s26, s45
	s_or_b32 s0, s19, s20
	s_ashr_i32 s2, s1, 31
	s_add_u32 s0, s1, s0
	s_addc_u32 s1, s2, 0
	s_lshl_b64 s[2:3], s[0:1], 11
	s_add_u32 s2, s33, s2
	s_addc_u32 s3, s34, s3
	s_lshl_b32 s18, s18, 7
	s_mov_b32 s21, s77
	s_add_u32 s2, s2, s18
	s_addc_u32 s3, s3, 0
	s_lshl_b64 s[20:21], s[20:21], 11
	s_add_u32 s24, s35, s20
	s_addc_u32 s25, s38, s21
	s_add_u32 s24, s24, s18
	s_addc_u32 s25, s25, 0
	s_add_u32 s18, s39, s20
	v_and_b32_e32 v241, 63, v34
	s_addc_u32 s21, s40, s21
	s_lshl_b32 s20, s26, 7
	s_add_u32 s20, s18, s20
	v_lshlrev_b32_e32 v0, 11, v241
	s_addc_u32 s21, s21, 0
	v_lshl_add_u64 v[2:3], s[24:25], 0, v[0:1]
	s_lshl_b32 s18, s44, 4
	v_bfe_u32 v0, v34, 2, 4
	s_lshl_b32 s24, s44, 3
	v_and_or_b32 v0, s18, 48, v0
	s_ashr_i32 s25, s24, 31
	v_lshlrev_b32_e32 v0, 11, v0
	s_ashr_i32 s18, s47, 3
	v_lshl_add_u64 v[220:221], s[24:25], 1, v[2:3]
	v_lshl_add_u64 v[2:3], s[20:21], 0, v[0:1]
	s_and_b32 s20, s18, 0xffffffe0
	s_ashr_i32 s21, s20, 31
	s_lshl_b32 s18, s44, 10
	v_lshlrev_b32_e32 v244, 3, v4
	s_cmp_lg_u32 0, -1
	v_lshl_add_u64 v[2:3], s[20:21], 1, v[2:3]
	v_and_b32_e32 v245, 24, v244
	s_cselect_b32 s20, 0, 0
	v_lshlrev_b32_e32 v0, 1, v245
	s_add_i32 s48, s18, s20
	s_mov_b32 s20, m0
	s_mov_b32 m0, s48
	s_nop 0
	global_load_lds_dwordx4 v[220:221], off
	s_mov_b32 m0, s20
	v_lshl_add_u64 v[222:223], v[2:3], 0, v[0:1]
	s_add_i32 s49, s48, 0x6000
	s_mov_b32 s20, m0
	s_mov_b32 m0, s49
	s_nop 0
	global_load_lds_dwordx4 v[222:223], off
	s_mov_b32 m0, s20
	v_and_b32_e32 v242, 31, v34
	v_lshl_add_u64 v[224:225], v[222:223], 0, s[80:81]
	s_add_i32 s50, s48, 0x8000
	s_mov_b32 s20, m0
	s_mov_b32 m0, s50
	s_nop 0
	global_load_lds_dwordx4 v[224:225], off
	s_mov_b32 m0, s20
	v_bfe_u32 v243, v34, 5, 1
	s_mov_b64 s[20:21], 0x20000
	v_lshlrev_b32_e32 v0, 11, v242
	v_lshl_add_u64 v[2:3], v[220:221], 0, s[20:21]
	s_add_i32 s20, s48, 0x2000
	s_mov_b32 s21, m0
	s_mov_b32 m0, s20
	s_nop 0
	global_load_lds_dwordx4 v[2:3], off
	s_mov_b32 m0, s21
	v_lshl_or_b32 v0, v243, 4, v0
	global_load_dwordx4 v[172:175], v0, s[2:3]
	global_load_dwordx4 v[168:171], v0, s[2:3] offset:32
	global_load_dwordx4 v[164:167], v0, s[2:3] offset:64
	global_load_dwordx4 v[156:159], v0, s[2:3] offset:96
	v_lshlrev_b32_e32 v0, 10, v243
	v_lshlrev_b32_e32 v2, 4, v242
	s_mov_b64 s[2:3], 0x40000
	v_add3_u32 v250, 0, v0, v2
	v_lshl_add_u64 v[2:3], v[220:221], 0, s[2:3]
	s_add_i32 s2, s48, 0x4000
	s_mov_b32 s3, m0
	s_mov_b32 m0, s2
	s_nop 0
	global_load_lds_dwordx4 v[2:3], off
	s_mov_b32 m0, s3
	s_waitcnt vmcnt(3) lgkmcnt(0)
	s_barrier
	ds_read_b128 v[2:5], v250
	ds_read_b128 v[18:21], v250 offset:512
	ds_read_b128 v[36:39], v250 offset:2048
	s_cmp_lg_u32 s27, 31
	s_cselect_b64 s[2:3], -1, 0
	s_and_b64 vcc, exec, s[2:3]
	s_waitcnt vmcnt(3) lgkmcnt(2)
	v_mfma_f32_32x32x16_bf16 v[2:17], v[2:5], v[172:175], 0
	s_waitcnt vmcnt(2) lgkmcnt(0)
	v_mfma_f32_32x32x16_bf16 v[2:17], v[36:39], v[168:171], v[2:17]
	ds_read_b128 v[36:39], v250 offset:2560
	v_mfma_f32_32x32x16_bf16 v[18:33], v[18:21], v[172:175], 0
	s_waitcnt lgkmcnt(0)
	v_mfma_f32_32x32x16_bf16 v[18:33], v[36:39], v[168:171], v[18:33]
	ds_read_b128 v[36:39], v250 offset:4096
	s_waitcnt vmcnt(1) lgkmcnt(0)
	v_mfma_f32_32x32x16_bf16 v[2:17], v[36:39], v[164:167], v[2:17]
	ds_read_b128 v[36:39], v250 offset:4608
	s_waitcnt lgkmcnt(0)
	v_mfma_f32_32x32x16_bf16 v[18:33], v[36:39], v[164:167], v[18:33]
	ds_read_b128 v[36:39], v250 offset:6144
	s_waitcnt vmcnt(0) lgkmcnt(0)
	v_mfma_f32_32x32x16_bf16 v[2:17], v[36:39], v[156:159], v[2:17]
	ds_read_b128 v[36:39], v250 offset:6656
	s_waitcnt lgkmcnt(0)
	v_mfma_f32_32x32x16_bf16 v[18:33], v[36:39], v[156:159], v[18:33]
	s_nop 15
	s_nop 7
	s_cbranch_vccnz .LBB0_1987
	s_cmp_lt_i32 s47, 0
	s_cselect_b64 vcc, -1, 0
	s_nop 5
	v_cndmask_b32_e32 v17, v17, v240, vcc
	v_cndmask_b32_e32 v16, v16, v240, vcc
	v_cndmask_b32_e32 v15, v15, v240, vcc
	v_cndmask_b32_e32 v14, v14, v240, vcc
	v_cndmask_b32_e32 v13, v13, v240, vcc
	v_cndmask_b32_e32 v12, v12, v240, vcc
	v_cndmask_b32_e32 v11, v11, v240, vcc
	v_cndmask_b32_e32 v10, v10, v240, vcc
	v_cndmask_b32_e32 v9, v9, v240, vcc
	v_cndmask_b32_e32 v8, v8, v240, vcc
	v_cndmask_b32_e32 v7, v7, v240, vcc
	v_cndmask_b32_e32 v6, v6, v240, vcc
	v_cndmask_b32_e32 v5, v5, v240, vcc
	v_cndmask_b32_e32 v4, v4, v240, vcc
	v_cndmask_b32_e32 v3, v3, v240, vcc
	v_cndmask_b32_e32 v2, v2, v240, vcc
	v_cndmask_b32_e32 v33, v33, v240, vcc
	v_cndmask_b32_e32 v32, v32, v240, vcc
	v_cndmask_b32_e32 v31, v31, v240, vcc
	v_cndmask_b32_e32 v30, v30, v240, vcc
	v_cndmask_b32_e32 v29, v29, v240, vcc
	v_cndmask_b32_e32 v28, v28, v240, vcc
	v_cndmask_b32_e32 v27, v27, v240, vcc
	v_cndmask_b32_e32 v26, v26, v240, vcc
	v_cndmask_b32_e32 v25, v25, v240, vcc
	v_cndmask_b32_e32 v24, v24, v240, vcc
	v_cndmask_b32_e32 v23, v23, v240, vcc
	v_cndmask_b32_e32 v22, v22, v240, vcc
	v_cndmask_b32_e32 v21, v21, v240, vcc
	v_cndmask_b32_e32 v20, v20, v240, vcc
	v_cndmask_b32_e32 v19, v19, v240, vcc
	v_cndmask_b32_e32 v18, v18, v240, vcc
